# FoX steady-state loop without visibility tests (step advance after the first MFMA, rescale block out of line) and the mid barrier after all 32 MFMAs of the MFMA half
# baseline (speedup 1.0000x reference)
.Lfx_body:
	s_cmp_lt_u32 s62, 0x4000005e
	s_cselect_b64 s[78:79], -1, 0
	s_andn2_b64 vcc, exec, s[78:79]
	s_cbranch_vccnz .Lfx_h1_done
	s_andn2_b64 vcc, exec, s[80:81]
	s_cbranch_vccnz .Lfx_h1_qonly
	s_add_i32 s64, s77, s51
	v_add_u32_e32 v10, s64, v183
	v_add_u32_e32 v11, s64, v184
	v_add_u32_e32 v12, s64, v185
	v_add_u32_e32 v13, s64, v186
	s_add_i32 s65, s76, s51
	v_add_u32_e32 v14, s65, v174
	s_lshl_b32 s66, s50, 2
	s_add_i32 s66, s66, s76
	v_lshl_add_u32 v0, v144, 2, s66
	v_add_u32_e32 v0, 0x10000, v0
	s_waitcnt lgkmcnt(6)
	v_mfma_f32_32x32x16_bf16 v[64:79], v[2:5], v[196:199], v[64:79]
	ds_read_b64_tr_b16 v[220:221], v11 offset:32768
	ds_read_b64_tr_b16 v[222:223], v11 offset:34816
	s_lshl_b32 s64, s41, 7
	s_add_i32 s66, s64, 0xffffff80
	s_max_i32 s66, s66, 0
	s_mov_b32 s67, 0
	s_lshl_b64 s[28:29], s[66:67], 8
	s_add_u32 s28, s27, s28
	s_addc_u32 s29, s38, s29
	s_lshl_b64 s[68:69], s[66:67], 2
	s_add_u32 s68, s70, s68
	s_addc_u32 s69, s71, s69
	s_lshl_b64 s[30:31], s[66:67], 8
	s_add_u32 s30, s23, s30
	s_addc_u32 s31, s24, s31
	ds_read_b128 v[96:99], v0
	s_waitcnt lgkmcnt(7)
	v_mfma_f32_32x32x16_bf16 v[64:79], v[6:9], v[204:207], v[64:79]
	ds_read_b64_tr_b16 v[224:225], v11 offset:36864
	ds_read_b64_tr_b16 v[226:227], v11 offset:38912
	s_add_i32 s33, s73, s77
	s_mov_b32 m0, s33
	s_nop 0
	global_load_lds_dwordx4 v163, s[28:29]
	ds_read_b128 v[100:103], v0 offset:32
	s_waitcnt lgkmcnt(8)
	v_mfma_f32_32x32x16_bf16 v[64:79], v[212:215], v[200:203], v[64:79]
	ds_read_b64_tr_b16 v[228:229], v11 offset:40960
	ds_read_b64_tr_b16 v[230:231], v11 offset:43008
	ds_read_b128 v[80:83], v0 offset:128
	s_waitcnt lgkmcnt(9)
	v_mfma_f32_32x32x16_bf16 v[64:79], v[216:219], v[208:211], v[64:79]
	ds_read_b64_tr_b16 v[232:233], v11 offset:45056
	ds_read_b64_tr_b16 v[234:235], v11 offset:47104
	ds_read_b128 v[84:87], v0 offset:160
	s_waitcnt lgkmcnt(10)
	v_mfma_f32_32x32x16_bf16 v[48:63], v[220:223], v[196:199], v[48:63]
	ds_read_b64_tr_b16 v[2:3], v12 offset:32768
	ds_read_b64_tr_b16 v[4:5], v12 offset:34816
	s_add_i32 m0, s33, 0x400
	s_nop 0
	global_load_lds_dwordx4 v189, s[28:29]
	ds_read_b128 v[104:107], v0 offset:64
	s_waitcnt lgkmcnt(10)
	v_mfma_f32_32x32x16_bf16 v[48:63], v[224:227], v[204:207], v[48:63]
	ds_read_b64_tr_b16 v[6:7], v12 offset:36864
	ds_read_b64_tr_b16 v[8:9], v12 offset:38912
	ds_read_b128 v[108:111], v0 offset:96
	s_waitcnt lgkmcnt(10)
	v_mfma_f32_32x32x16_bf16 v[48:63], v[228:231], v[200:203], v[48:63]
	ds_read_b64_tr_b16 v[212:213], v12 offset:40960
	ds_read_b64_tr_b16 v[214:215], v12 offset:43008
	ds_read_b128 v[88:91], v0 offset:192
	s_waitcnt lgkmcnt(10)
	v_mfma_f32_32x32x16_bf16 v[48:63], v[232:235], v[208:211], v[48:63]
	ds_read_b64_tr_b16 v[216:217], v12 offset:45056
	ds_read_b64_tr_b16 v[218:219], v12 offset:47104
	s_add_i32 m0, s33, 0x800
	s_nop 0
	global_load_lds_dwordx4 v190, s[28:29]
	ds_read_b128 v[92:95], v0 offset:224
	s_waitcnt lgkmcnt(10)
	v_mfma_f32_32x32x16_bf16 v[32:47], v[2:5], v[196:199], v[32:47]
	ds_read_b64_tr_b16 v[220:221], v13 offset:32768
	ds_read_b64_tr_b16 v[222:223], v13 offset:34816
	s_waitcnt lgkmcnt(9)
	v_mfma_f32_32x32x16_bf16 v[32:47], v[6:9], v[204:207], v[32:47]
	ds_read_b64_tr_b16 v[224:225], v13 offset:36864
	ds_read_b64_tr_b16 v[226:227], v13 offset:38912
	s_waitcnt lgkmcnt(8)
	v_mfma_f32_32x32x16_bf16 v[32:47], v[212:215], v[200:203], v[32:47]
	ds_read_b64_tr_b16 v[228:229], v13 offset:40960
	ds_read_b64_tr_b16 v[230:231], v13 offset:43008
	s_add_i32 m0, s33, 0xc00
	s_nop 0
	global_load_lds_dwordx4 v191, s[28:29]
	s_waitcnt lgkmcnt(7)
	v_mfma_f32_32x32x16_bf16 v[32:47], v[216:219], v[208:211], v[32:47]
	ds_read_b64_tr_b16 v[232:233], v13 offset:45056
	ds_read_b64_tr_b16 v[234:235], v13 offset:47104
	s_waitcnt lgkmcnt(6)
	v_mfma_f32_32x32x16_bf16 v[16:31], v[220:223], v[196:199], v[16:31]
	v_add_u32_e32 v15, v14, v175
	ds_read_b128 v[2:5], v15
	s_waitcnt lgkmcnt(5)
	v_mfma_f32_32x32x16_bf16 v[16:31], v[224:227], v[204:207], v[16:31]
	ds_read_b128 v[6:9], v15 offset:8192
	s_add_i32 m0, s72, s77
	s_nop 0
	global_load_lds_dword v172, s[68:69]
	s_waitcnt lgkmcnt(4)
	v_mfma_f32_32x32x16_bf16 v[16:31], v[228:231], v[200:203], v[16:31]
	v_add_u32_e32 v15, v14, v176
	ds_read_b128 v[212:215], v15
	s_waitcnt lgkmcnt(3)
	v_mfma_f32_32x32x16_bf16 v[16:31], v[232:235], v[208:211], v[16:31]
	ds_read_b128 v[216:219], v15 offset:8192
	s_waitcnt lgkmcnt(3)
	v_mfma_f32_32x32x16_bf16 v[96:111], v[2:5], v[112:115], v[96:111]
	v_add_u32_e32 v15, v14, v177
	ds_read_b128 v[220:223], v15
	s_waitcnt lgkmcnt(3)
	v_mfma_f32_32x32x16_bf16 v[80:95], v[6:9], v[112:115], v[80:95]
	ds_read_b128 v[224:227], v15 offset:8192
	s_waitcnt lgkmcnt(3)
	v_mfma_f32_32x32x16_bf16 v[96:111], v[212:215], v[116:119], v[96:111]
	v_add_u32_e32 v15, v14, v178
	ds_read_b128 v[228:231], v15
	s_waitcnt lgkmcnt(3)
	v_mfma_f32_32x32x16_bf16 v[80:95], v[216:219], v[116:119], v[80:95]
	ds_read_b128 v[232:235], v15 offset:8192
	s_waitcnt lgkmcnt(3)
	v_mfma_f32_32x32x16_bf16 v[96:111], v[220:223], v[120:123], v[96:111]
	v_add_u32_e32 v15, v14, v179
	ds_read_b128 v[2:5], v15
	s_waitcnt lgkmcnt(3)
	v_mfma_f32_32x32x16_bf16 v[80:95], v[224:227], v[120:123], v[80:95]
	ds_read_b128 v[6:9], v15 offset:8192
	s_waitcnt lgkmcnt(3)
	v_mfma_f32_32x32x16_bf16 v[96:111], v[228:231], v[124:127], v[96:111]
	v_add_u32_e32 v15, v14, v180
	ds_read_b128 v[212:215], v15
	s_waitcnt lgkmcnt(3)
	v_mfma_f32_32x32x16_bf16 v[80:95], v[232:235], v[124:127], v[80:95]
	ds_read_b128 v[216:219], v15 offset:8192
	s_waitcnt lgkmcnt(3)
	v_mfma_f32_32x32x16_bf16 v[96:111], v[2:5], v[128:131], v[96:111]
	v_add_u32_e32 v15, v14, v181
	ds_read_b128 v[220:223], v15
	s_waitcnt lgkmcnt(3)
	v_mfma_f32_32x32x16_bf16 v[80:95], v[6:9], v[128:131], v[80:95]
	ds_read_b128 v[224:227], v15 offset:8192
	s_waitcnt lgkmcnt(3)
	v_mfma_f32_32x32x16_bf16 v[96:111], v[212:215], v[132:135], v[96:111]
	v_add_u32_e32 v15, v14, v182
	ds_read_b128 v[228:231], v15
	s_waitcnt lgkmcnt(3)
	v_mfma_f32_32x32x16_bf16 v[80:95], v[216:219], v[132:135], v[80:95]
	ds_read_b128 v[232:235], v15 offset:8192
	s_waitcnt lgkmcnt(3)
	v_mfma_f32_32x32x16_bf16 v[96:111], v[220:223], v[136:139], v[96:111]
	s_waitcnt lgkmcnt(2)
	v_mfma_f32_32x32x16_bf16 v[80:95], v[224:227], v[136:139], v[80:95]
	s_waitcnt lgkmcnt(1)
	v_mfma_f32_32x32x16_bf16 v[96:111], v[228:231], v[140:143], v[96:111]
	s_waitcnt lgkmcnt(0)
	v_mfma_f32_32x32x16_bf16 v[80:95], v[232:235], v[140:143], v[80:95]
	s_waitcnt vmcnt(5)
	s_barrier
	s_nop 7
	s_branch .Lfx_h1_joined
.Lfx_h1_qonly:
	s_lshl_b32 s64, s41, 7
	s_add_i32 s66, s64, 0xffffff80
	s_max_i32 s66, s66, 0
	s_mov_b32 s67, 0
	s_lshl_b64 s[28:29], s[66:67], 8
	s_add_u32 s28, s27, s28
	s_addc_u32 s29, s38, s29
	s_lshl_b64 s[68:69], s[66:67], 2
	s_add_u32 s68, s70, s68
	s_addc_u32 s69, s71, s69
	s_lshl_b64 s[30:31], s[66:67], 8
	s_add_u32 s30, s23, s30
	s_addc_u32 s31, s24, s31
	s_add_i32 s65, s76, s51
	v_add_u32_e32 v14, s65, v174
	s_lshl_b32 s66, s50, 2
	s_add_i32 s66, s66, s76
	v_lshl_add_u32 v0, v144, 2, s66
	v_add_u32_e32 v0, 0x10000, v0
	ds_read_b128 v[96:99], v0
	ds_read_b128 v[100:103], v0 offset:32
	ds_read_b128 v[80:83], v0 offset:128
	ds_read_b128 v[84:87], v0 offset:160
	ds_read_b128 v[104:107], v0 offset:64
	ds_read_b128 v[108:111], v0 offset:96
	ds_read_b128 v[88:91], v0 offset:192
	ds_read_b128 v[92:95], v0 offset:224
	v_add_u32_e32 v15, v14, v175
	ds_read_b128 v[2:5], v15
	ds_read_b128 v[6:9], v15 offset:8192
	v_add_u32_e32 v15, v14, v176
	ds_read_b128 v[212:215], v15
	ds_read_b128 v[216:219], v15 offset:8192
	s_waitcnt lgkmcnt(3)
	v_mfma_f32_32x32x16_bf16 v[96:111], v[2:5], v[112:115], v[96:111]
	v_add_u32_e32 v15, v14, v177
	ds_read_b128 v[220:223], v15
	s_waitcnt lgkmcnt(3)
	v_mfma_f32_32x32x16_bf16 v[80:95], v[6:9], v[112:115], v[80:95]
	ds_read_b128 v[224:227], v15 offset:8192
	s_add_i32 s33, s73, s77
	s_mov_b32 m0, s33
	s_nop 0
	global_load_lds_dwordx4 v163, s[28:29]
	s_waitcnt lgkmcnt(3)
	v_mfma_f32_32x32x16_bf16 v[96:111], v[212:215], v[116:119], v[96:111]
	v_add_u32_e32 v15, v14, v178
	ds_read_b128 v[228:231], v15
	s_waitcnt lgkmcnt(3)
	v_mfma_f32_32x32x16_bf16 v[80:95], v[216:219], v[116:119], v[80:95]
	ds_read_b128 v[232:235], v15 offset:8192
	s_add_i32 m0, s33, 0x400
	s_nop 0
	global_load_lds_dwordx4 v189, s[28:29]
	s_waitcnt lgkmcnt(3)
	v_mfma_f32_32x32x16_bf16 v[96:111], v[220:223], v[120:123], v[96:111]
	v_add_u32_e32 v15, v14, v179
	ds_read_b128 v[2:5], v15
	s_waitcnt lgkmcnt(3)
	v_mfma_f32_32x32x16_bf16 v[80:95], v[224:227], v[120:123], v[80:95]
	ds_read_b128 v[6:9], v15 offset:8192
	s_add_i32 m0, s33, 0x800
	s_nop 0
	global_load_lds_dwordx4 v190, s[28:29]
	s_waitcnt lgkmcnt(3)
	v_mfma_f32_32x32x16_bf16 v[96:111], v[228:231], v[124:127], v[96:111]
	v_add_u32_e32 v15, v14, v180
	ds_read_b128 v[212:215], v15
	s_waitcnt lgkmcnt(3)
	v_mfma_f32_32x32x16_bf16 v[80:95], v[232:235], v[124:127], v[80:95]
	ds_read_b128 v[216:219], v15 offset:8192
	s_add_i32 m0, s33, 0xc00
	s_nop 0
	global_load_lds_dwordx4 v191, s[28:29]
	s_waitcnt lgkmcnt(3)
	v_mfma_f32_32x32x16_bf16 v[96:111], v[2:5], v[128:131], v[96:111]
	v_add_u32_e32 v15, v14, v181
	ds_read_b128 v[220:223], v15
	s_waitcnt lgkmcnt(3)
	v_mfma_f32_32x32x16_bf16 v[80:95], v[6:9], v[128:131], v[80:95]
	ds_read_b128 v[224:227], v15 offset:8192
	s_add_i32 m0, s72, s77
	s_nop 0
	global_load_lds_dword v172, s[68:69]
	s_waitcnt lgkmcnt(3)
	v_mfma_f32_32x32x16_bf16 v[96:111], v[212:215], v[132:135], v[96:111]
	v_add_u32_e32 v15, v14, v182
	ds_read_b128 v[228:231], v15
	s_waitcnt lgkmcnt(3)
	v_mfma_f32_32x32x16_bf16 v[80:95], v[216:219], v[132:135], v[80:95]
	ds_read_b128 v[232:235], v15 offset:8192
	s_waitcnt lgkmcnt(3)
	v_mfma_f32_32x32x16_bf16 v[96:111], v[220:223], v[136:139], v[96:111]
	s_waitcnt lgkmcnt(2)
	v_mfma_f32_32x32x16_bf16 v[80:95], v[224:227], v[136:139], v[80:95]
	s_waitcnt lgkmcnt(1)
	v_mfma_f32_32x32x16_bf16 v[96:111], v[228:231], v[140:143], v[96:111]
	s_waitcnt lgkmcnt(0)
	v_mfma_f32_32x32x16_bf16 v[80:95], v[232:235], v[140:143], v[80:95]
	s_waitcnt vmcnt(5)
	s_barrier
	s_add_i32 s29, s62, 0xc0000001
	s_cmp_gt_u32 s29, 0xc000005d
	s_cbranch_scc1 .Lfx_nomask_q
	s_nop 11
	v_add_u32_e32 v0, s62, v147
	v_subrev_u32_e32 v2, 30, v0
	v_cmp_gt_u32_e32 vcc, 2.0, v2
	v_add_u32_e32 v2, 0xbfffffc2, v0
	s_nop 3
	v_cndmask_b32_e32 v96, v187, v96, vcc
	v_cmp_lt_u32_e32 vcc, s17, v2
	v_subrev_u32_e32 v2, 31, v0
	s_nop 0
	v_cndmask_b32_e32 v80, v187, v80, vcc
	v_cmp_gt_u32_e32 vcc, 2.0, v2
	v_add_u32_e32 v2, 0xbfffffc1, v0
	s_nop 0
	v_cndmask_b32_e32 v97, v187, v97, vcc
	v_cmp_lt_u32_e32 vcc, s17, v2
	v_subrev_u32_e32 v2, 32, v0
	s_nop 0
	v_cndmask_b32_e32 v81, v187, v81, vcc
	v_cmp_gt_u32_e32 vcc, 2.0, v2
	v_add_u32_e32 v2, 0xbfffffc0, v0
	s_nop 0
	v_cndmask_b32_e32 v98, v187, v98, vcc
	v_cmp_lt_u32_e32 vcc, s17, v2
	v_subrev_u32_e32 v2, 33, v0
	s_nop 0
	v_cndmask_b32_e32 v82, v187, v82, vcc
	v_cmp_gt_u32_e32 vcc, 2.0, v2
	v_add_u32_e32 v2, 0xbfffffbf, v0
	s_nop 0
	v_cndmask_b32_e32 v99, v187, v99, vcc
	v_cmp_lt_u32_e32 vcc, s17, v2
	v_subrev_u32_e32 v2, 38, v0
	s_nop 0
	v_cndmask_b32_e32 v83, v187, v83, vcc
	v_cmp_gt_u32_e32 vcc, 2.0, v2
	v_add_u32_e32 v2, 0xbfffffba, v0
	s_nop 0
	v_cndmask_b32_e32 v100, v187, v100, vcc
	v_cmp_lt_u32_e32 vcc, s17, v2
	v_subrev_u32_e32 v2, 39, v0
	s_nop 0
	v_cndmask_b32_e32 v84, v187, v84, vcc
	v_cmp_gt_u32_e32 vcc, 2.0, v2
	v_add_u32_e32 v2, 0xbfffffb9, v0
	s_nop 0
	v_cndmask_b32_e32 v101, v187, v101, vcc
	v_cmp_lt_u32_e32 vcc, s17, v2
	v_subrev_u32_e32 v2, 40, v0
	s_nop 0
	v_cndmask_b32_e32 v85, v187, v85, vcc
	v_cmp_gt_u32_e32 vcc, 2.0, v2
	v_add_u32_e32 v2, 0xbfffffb8, v0
	s_nop 0
	v_cndmask_b32_e32 v102, v187, v102, vcc
	v_cmp_lt_u32_e32 vcc, s17, v2
	v_subrev_u32_e32 v2, 41, v0
	s_nop 0
	v_cndmask_b32_e32 v86, v187, v86, vcc
	v_cmp_gt_u32_e32 vcc, 2.0, v2
	v_add_u32_e32 v2, 0xbfffffb7, v0
	s_nop 0
	v_cndmask_b32_e32 v103, v187, v103, vcc
	v_cmp_lt_u32_e32 vcc, s17, v2
	v_subrev_u32_e32 v2, 46, v0
	s_nop 0
	v_cndmask_b32_e32 v87, v187, v87, vcc
	v_cmp_gt_u32_e32 vcc, 2.0, v2
	v_add_u32_e32 v2, 0xbfffffb2, v0
	s_nop 0
	v_cndmask_b32_e32 v104, v187, v104, vcc
	v_cmp_lt_u32_e32 vcc, s17, v2
	v_subrev_u32_e32 v2, 47, v0
	s_nop 0
	v_cndmask_b32_e32 v88, v187, v88, vcc
	v_cmp_gt_u32_e32 vcc, 2.0, v2
	v_add_u32_e32 v2, 0xbfffffb1, v0
	s_nop 0
	v_cndmask_b32_e32 v105, v187, v105, vcc
	v_cmp_lt_u32_e32 vcc, s17, v2
	v_subrev_u32_e32 v2, 48, v0
	s_nop 0
	v_cndmask_b32_e32 v89, v187, v89, vcc
	v_cmp_gt_u32_e32 vcc, 2.0, v2
	v_add_u32_e32 v2, 0xbfffffb0, v0
	s_nop 0
	v_cndmask_b32_e32 v106, v187, v106, vcc
	v_cmp_lt_u32_e32 vcc, s17, v2
	v_subrev_u32_e32 v2, 49, v0
	s_nop 0
	v_cndmask_b32_e32 v90, v187, v90, vcc
	v_cmp_gt_u32_e32 vcc, 2.0, v2
	v_add_u32_e32 v2, 0xbfffffaf, v0
	s_nop 0
	v_cndmask_b32_e32 v107, v187, v107, vcc
	v_cmp_lt_u32_e32 vcc, s17, v2
	v_subrev_u32_e32 v2, 54, v0
	s_nop 0
	v_cndmask_b32_e32 v91, v187, v91, vcc
	v_cmp_gt_u32_e32 vcc, 2.0, v2
	v_add_u32_e32 v2, 0xbfffffaa, v0
	s_nop 0
	v_cndmask_b32_e32 v108, v187, v108, vcc
	v_cmp_lt_u32_e32 vcc, s17, v2
	v_subrev_u32_e32 v2, 55, v0
	s_nop 0
	v_cndmask_b32_e32 v92, v187, v92, vcc
	v_cmp_gt_u32_e32 vcc, 2.0, v2
	v_add_u32_e32 v2, 0xbfffffa9, v0
	s_nop 0
	v_cndmask_b32_e32 v109, v187, v109, vcc
	v_cmp_lt_u32_e32 vcc, s17, v2
	v_subrev_u32_e32 v2, 56, v0
	s_nop 0
	v_cndmask_b32_e32 v93, v187, v93, vcc
	v_cmp_gt_u32_e32 vcc, 2.0, v2
	v_add_u32_e32 v2, 0xbfffffa8, v0
	s_nop 0
	v_cndmask_b32_e32 v110, v187, v110, vcc
	v_cmp_lt_u32_e32 vcc, s17, v2
	v_subrev_u32_e32 v2, 57, v0
	v_add_u32_e32 v0, 0xbfffffa7, v0
	v_cndmask_b32_e32 v94, v187, v94, vcc
	v_cmp_gt_u32_e32 vcc, 2.0, v2
	s_nop 1
	v_cndmask_b32_e32 v111, v187, v111, vcc
	v_cmp_lt_u32_e32 vcc, s17, v0
	s_nop 1
	v_cndmask_b32_e32 v95, v187, v95, vcc

.Lfx_h2_done:
	s_barrier
	s_add_i32 s63, s63, 1
	s_addk_i32 s62, 0x80
	s_mov_b64 s[80:81], s[78:79]
	s_cmp_eq_u32 s41, 0
	s_cbranch_scc1 .Lfx_exit_adv
	s_cmp_ge_u32 s63, 2
	s_cbranch_scc1 .Lfx_fast
	s_add_i32 s41, s41, -1
	s_xor_b32 s76, s76, 0x10200
	s_xor_b32 s77, s77, 0x10200
	s_branch .Lfx_body
.Lfx_fast:
	s_waitcnt lgkmcnt(6)
	v_mfma_f32_32x32x16_bf16 v[64:79], v[2:5], v[196:199], v[64:79]
	s_add_i32 s41, s41, -1
	s_xor_b32 s76, s76, 0x10200
	s_xor_b32 s77, s77, 0x10200
	s_add_i32 s64, s77, s51
	v_add_u32_e32 v11, s64, v184
	v_add_u32_e32 v12, s64, v185
	v_add_u32_e32 v13, s64, v186
	s_add_i32 s65, s76, s51
	v_add_u32_e32 v14, s65, v174
	s_lshl_b32 s66, s50, 2
	s_add_i32 s66, s66, s76
	v_lshl_add_u32 v0, v144, 2, s66
	v_add_u32_e32 v0, 0x10000, v0
	ds_read_b64_tr_b16 v[220:221], v11 offset:32768
	ds_read_b64_tr_b16 v[222:223], v11 offset:34816
	ds_read_b128 v[96:99], v0
	s_waitcnt lgkmcnt(7)
	v_mfma_f32_32x32x16_bf16 v[64:79], v[6:9], v[204:207], v[64:79]
	ds_read_b64_tr_b16 v[224:225], v11 offset:36864
	ds_read_b64_tr_b16 v[226:227], v11 offset:38912
	s_lshl_b32 s64, s41, 7
	s_add_i32 s66, s64, 0xffffff80
	s_max_i32 s66, s66, 0
	s_mov_b32 s67, 0
	s_lshl_b64 s[28:29], s[66:67], 8
	s_add_u32 s28, s27, s28
	s_addc_u32 s29, s38, s29
	ds_read_b128 v[100:103], v0 offset:32
	s_waitcnt lgkmcnt(8)
	v_mfma_f32_32x32x16_bf16 v[64:79], v[212:215], v[200:203], v[64:79]
	ds_read_b64_tr_b16 v[228:229], v11 offset:40960
	ds_read_b64_tr_b16 v[230:231], v11 offset:43008
	s_lshl_b64 s[68:69], s[66:67], 2
	s_add_u32 s68, s70, s68
	s_addc_u32 s69, s71, s69
	s_lshl_b64 s[30:31], s[66:67], 8
	s_add_u32 s30, s23, s30
	s_addc_u32 s31, s24, s31
	ds_read_b128 v[80:83], v0 offset:128
	s_waitcnt lgkmcnt(9)
	v_mfma_f32_32x32x16_bf16 v[64:79], v[216:219], v[208:211], v[64:79]
	ds_read_b64_tr_b16 v[232:233], v11 offset:45056
	ds_read_b64_tr_b16 v[234:235], v11 offset:47104
	s_add_i32 s33, s73, s77
	s_mov_b32 m0, s33
	s_nop 0
	global_load_lds_dwordx4 v163, s[28:29]
	ds_read_b128 v[84:87], v0 offset:160
	s_waitcnt lgkmcnt(10)
	v_mfma_f32_32x32x16_bf16 v[48:63], v[220:223], v[196:199], v[48:63]
	ds_read_b64_tr_b16 v[2:3], v12 offset:32768
	ds_read_b64_tr_b16 v[4:5], v12 offset:34816
	ds_read_b128 v[104:107], v0 offset:64
	s_waitcnt lgkmcnt(10)
	v_mfma_f32_32x32x16_bf16 v[48:63], v[224:227], v[204:207], v[48:63]
	ds_read_b64_tr_b16 v[6:7], v12 offset:36864
	ds_read_b64_tr_b16 v[8:9], v12 offset:38912
	ds_read_b128 v[108:111], v0 offset:96
	s_waitcnt lgkmcnt(10)
	v_mfma_f32_32x32x16_bf16 v[48:63], v[228:231], v[200:203], v[48:63]
	ds_read_b64_tr_b16 v[212:213], v12 offset:40960
	ds_read_b64_tr_b16 v[214:215], v12 offset:43008
	s_add_i32 m0, s33, 0x400
	s_nop 0
	global_load_lds_dwordx4 v189, s[28:29]
	ds_read_b128 v[88:91], v0 offset:192
	s_waitcnt lgkmcnt(10)
	v_mfma_f32_32x32x16_bf16 v[48:63], v[232:235], v[208:211], v[48:63]
	ds_read_b64_tr_b16 v[216:217], v12 offset:45056
	ds_read_b64_tr_b16 v[218:219], v12 offset:47104
	ds_read_b128 v[92:95], v0 offset:224
	s_waitcnt lgkmcnt(10)
	v_mfma_f32_32x32x16_bf16 v[32:47], v[2:5], v[196:199], v[32:47]
	ds_read_b64_tr_b16 v[220:221], v13 offset:32768
	ds_read_b64_tr_b16 v[222:223], v13 offset:34816
	s_waitcnt lgkmcnt(9)
	v_mfma_f32_32x32x16_bf16 v[32:47], v[6:9], v[204:207], v[32:47]
	ds_read_b64_tr_b16 v[224:225], v13 offset:36864
	ds_read_b64_tr_b16 v[226:227], v13 offset:38912
	s_add_i32 m0, s33, 0x800
	s_nop 0
	global_load_lds_dwordx4 v190, s[28:29]
	s_waitcnt lgkmcnt(8)
	v_mfma_f32_32x32x16_bf16 v[32:47], v[212:215], v[200:203], v[32:47]
	ds_read_b64_tr_b16 v[228:229], v13 offset:40960
	ds_read_b64_tr_b16 v[230:231], v13 offset:43008
	s_waitcnt lgkmcnt(7)
	v_mfma_f32_32x32x16_bf16 v[32:47], v[216:219], v[208:211], v[32:47]
	ds_read_b64_tr_b16 v[232:233], v13 offset:45056
	ds_read_b64_tr_b16 v[234:235], v13 offset:47104
	s_waitcnt lgkmcnt(6)
	v_mfma_f32_32x32x16_bf16 v[16:31], v[220:223], v[196:199], v[16:31]
	v_add_u32_e32 v15, v14, v175
	ds_read_b128 v[2:5], v15
	s_add_i32 m0, s33, 0xc00
	s_nop 0
	global_load_lds_dwordx4 v191, s[28:29]
	s_waitcnt lgkmcnt(5)
	v_mfma_f32_32x32x16_bf16 v[16:31], v[224:227], v[204:207], v[16:31]
	ds_read_b128 v[6:9], v15 offset:8192
	s_waitcnt lgkmcnt(4)
	v_mfma_f32_32x32x16_bf16 v[16:31], v[228:231], v[200:203], v[16:31]
	v_add_u32_e32 v15, v14, v176
	ds_read_b128 v[212:215], v15
	s_waitcnt lgkmcnt(3)
	v_mfma_f32_32x32x16_bf16 v[16:31], v[232:235], v[208:211], v[16:31]
	ds_read_b128 v[216:219], v15 offset:8192
	s_add_i32 m0, s72, s77
	s_nop 0
	global_load_lds_dword v172, s[68:69]
	s_waitcnt lgkmcnt(3)
	v_mfma_f32_32x32x16_bf16 v[96:111], v[2:5], v[112:115], v[96:111]
	v_add_u32_e32 v15, v14, v177
	ds_read_b128 v[220:223], v15
	s_waitcnt lgkmcnt(3)
	v_mfma_f32_32x32x16_bf16 v[80:95], v[6:9], v[112:115], v[80:95]
	ds_read_b128 v[224:227], v15 offset:8192
	s_waitcnt lgkmcnt(3)
	v_mfma_f32_32x32x16_bf16 v[96:111], v[212:215], v[116:119], v[96:111]
	v_add_u32_e32 v15, v14, v178
	ds_read_b128 v[228:231], v15
	s_waitcnt lgkmcnt(3)
	v_mfma_f32_32x32x16_bf16 v[80:95], v[216:219], v[116:119], v[80:95]
	ds_read_b128 v[232:235], v15 offset:8192
	s_waitcnt lgkmcnt(3)
	v_mfma_f32_32x32x16_bf16 v[96:111], v[220:223], v[120:123], v[96:111]
	v_add_u32_e32 v15, v14, v179
	ds_read_b128 v[2:5], v15
	s_waitcnt lgkmcnt(3)
	v_mfma_f32_32x32x16_bf16 v[80:95], v[224:227], v[120:123], v[80:95]
	ds_read_b128 v[6:9], v15 offset:8192
	s_waitcnt lgkmcnt(3)
	v_mfma_f32_32x32x16_bf16 v[96:111], v[228:231], v[124:127], v[96:111]
	v_add_u32_e32 v15, v14, v180
	ds_read_b128 v[212:215], v15
	s_waitcnt lgkmcnt(3)
	v_mfma_f32_32x32x16_bf16 v[80:95], v[232:235], v[124:127], v[80:95]
	ds_read_b128 v[216:219], v15 offset:8192
	s_waitcnt lgkmcnt(3)
	v_mfma_f32_32x32x16_bf16 v[96:111], v[2:5], v[128:131], v[96:111]
	v_add_u32_e32 v15, v14, v181
	ds_read_b128 v[220:223], v15
	s_waitcnt lgkmcnt(3)
	v_mfma_f32_32x32x16_bf16 v[80:95], v[6:9], v[128:131], v[80:95]
	ds_read_b128 v[224:227], v15 offset:8192
	s_waitcnt lgkmcnt(3)
	v_mfma_f32_32x32x16_bf16 v[96:111], v[212:215], v[132:135], v[96:111]
	v_add_u32_e32 v15, v14, v182
	ds_read_b128 v[228:231], v15
	s_waitcnt lgkmcnt(3)
	v_mfma_f32_32x32x16_bf16 v[80:95], v[216:219], v[132:135], v[80:95]
	ds_read_b128 v[232:235], v15 offset:8192
	s_waitcnt lgkmcnt(3)
	v_mfma_f32_32x32x16_bf16 v[96:111], v[220:223], v[136:139], v[96:111]
	s_waitcnt lgkmcnt(2)
	v_mfma_f32_32x32x16_bf16 v[80:95], v[224:227], v[136:139], v[80:95]
	s_waitcnt lgkmcnt(1)
	v_mfma_f32_32x32x16_bf16 v[96:111], v[228:231], v[140:143], v[96:111]
	s_waitcnt lgkmcnt(0)
	v_mfma_f32_32x32x16_bf16 v[80:95], v[232:235], v[140:143], v[80:95]
	s_waitcnt vmcnt(5)
	s_barrier
	s_nop 8
	s_add_i32 m0, s74, s77
	s_nop 0
	global_load_lds_dwordx4 v188, s[30:31]
	v_max3_f32 v0, v96, v97, v80
	v_max3_f32 v2, v98, v99, v81
	v_max3_f32 v0, v0, v82, v83
	v_max3_f32 v2, v2, v102, v103
	v_max3_f32 v0, v0, v100, v101
	v_max3_f32 v2, v2, v86, v87
	v_max3_f32 v0, v0, v84, v85
	v_max3_f32 v2, v2, v106, v107
	v_max3_f32 v0, v0, v104, v105
	v_max3_f32 v2, v2, v90, v91
	v_max3_f32 v0, v0, v88, v89
	v_max3_f32 v2, v2, v110, v111
	v_max3_f32 v0, v0, v108, v109
	v_max3_f32 v2, v2, v94, v95
	v_max3_f32 v0, v0, v92, v93
	v_max_f32_e32 v2, v2, v2
	v_max_f32_e32 v0, v0, v0
	v_max_f32_e32 v0, v0, v2
	v_mov_b32_e32 v2, v0
	s_nop 1
	v_permlane32_swap_b32_e32 v0, v2
	v_max_f32_e32 v2, v2, v2
	v_max_f32_e32 v0, v0, v0
	v_max_f32_e32 v0, v0, v2
	v_add_f32_e32 v2, 0x41000000, v192
	v_cmp_gt_f32_e32 vcc, v0, v2
	s_cbranch_vccnz .Lfx_resc_fv
.Lfx_sm_exp_fv:
	v_sub_f32_e32 v0, v96, v192
	v_exp_f32_e32 v193, v0
	v_sub_f32_e32 v0, v80, v192
	v_exp_f32_e32 v194, v0
	v_sub_f32_e32 v0, v97, v192
	global_load_lds_dwordx4 v188, s[30:31] offset:1024
	v_exp_f32_e32 v2, v0
	v_sub_f32_e32 v0, v81, v192
	v_exp_f32_e32 v0, v0
	v_add_f32_e32 v3, v193, v194
	v_add_f32_e32 v4, v2, v0
	v_add_f32_e32 v5, v3, v1
	s_nop 0
	v_add_f32_e32 v9, v4, v5
	v_sub_f32_e32 v3, v98, v192
	v_sub_f32_e32 v4, v82, v192
	v_exp_f32_e32 v3, v3
	v_exp_f32_e32 v98, v4
	v_sub_f32_e32 v4, v99, v192
	v_sub_f32_e32 v5, v83, v192
	v_exp_f32_e32 v4, v4
	v_exp_f32_e32 v8, v5
	v_add_f32_e32 v5, v3, v98
	v_cvt_pk_bf16_f32 v196, v193, v2
	v_cvt_pk_bf16_f32 v197, v3, v4
	v_add_f32_e32 v6, v4, v8
	v_add_f32_e32 v7, v5, v9
	v_sub_f32_e32 v5, v100, v192
	v_add_f32_e32 v11, v6, v7
	v_sub_f32_e32 v6, v84, v192
	v_exp_f32_e32 v5, v5
	v_exp_f32_e32 v9, v6
	v_sub_f32_e32 v6, v101, v192
	v_sub_f32_e32 v7, v85, v192
	v_exp_f32_e32 v6, v6
	v_exp_f32_e32 v10, v7
	global_load_lds_dwordx4 v188, s[30:31] offset:2048
	v_add_f32_e32 v7, v5, v9
	v_cvt_pk_bf16_f32 v198, v5, v6
	v_add_f32_e32 v12, v6, v10
	v_add_f32_e32 v13, v7, v11
	v_sub_f32_e32 v7, v102, v192
	v_add_f32_e32 v13, v12, v13
	v_sub_f32_e32 v11, v86, v192
	v_sub_f32_e32 v12, v103, v192
	v_exp_f32_e32 v7, v7
	v_exp_f32_e32 v11, v11
	v_exp_f32_e32 v14, v12
	v_sub_f32_e32 v12, v87, v192
	v_exp_f32_e32 v12, v12
	v_add_f32_e32 v15, v7, v11
	v_cvt_pk_bf16_f32 v199, v7, v14
	v_cvt_pk_bf16_f32 v200, v194, v0
	v_add_f32_e32 v80, v14, v12
	v_add_f32_e32 v81, v15, v13
	v_sub_f32_e32 v13, v104, v192
	v_add_f32_e32 v81, v80, v81
	v_sub_f32_e32 v15, v88, v192
	v_sub_f32_e32 v80, v105, v192
	v_exp_f32_e32 v13, v13
	v_exp_f32_e32 v15, v15
	v_exp_f32_e32 v82, v80
	v_sub_f32_e32 v80, v89, v192
	v_exp_f32_e32 v80, v80
	v_add_f32_e32 v83, v13, v15
	v_cvt_pk_bf16_f32 v201, v98, v8
	v_cvt_pk_bf16_f32 v202, v9, v10
	global_load_lds_dwordx4 v188, s[30:31] offset:3072
	v_add_f32_e32 v84, v82, v80
	v_add_f32_e32 v85, v83, v81
	v_sub_f32_e32 v81, v106, v192
	v_add_f32_e32 v85, v84, v85
	v_sub_f32_e32 v83, v90, v192
	v_sub_f32_e32 v84, v107, v192
	v_exp_f32_e32 v81, v81
	v_exp_f32_e32 v83, v83
	v_exp_f32_e32 v86, v84
	v_sub_f32_e32 v84, v91, v192
	v_exp_f32_e32 v84, v84
	v_add_f32_e32 v87, v81, v83
	v_cvt_pk_bf16_f32 v203, v11, v12
	v_cvt_pk_bf16_f32 v204, v13, v82
	v_add_f32_e32 v88, v86, v84
	v_add_f32_e32 v89, v87, v85
	v_sub_f32_e32 v85, v108, v192
	v_add_f32_e32 v89, v88, v89
	v_sub_f32_e32 v87, v92, v192
	v_sub_f32_e32 v88, v109, v192
	v_exp_f32_e32 v85, v85
	v_exp_f32_e32 v87, v87
	v_exp_f32_e32 v90, v88
	s_add_i32 s64, s76, s51
	v_add_u32_e32 v10, s64, v183
	ds_read_b64_tr_b16 v[2:3], v10 offset:32768
	ds_read_b64_tr_b16 v[4:5], v10 offset:34816
	ds_read_b64_tr_b16 v[6:7], v10 offset:36864
	ds_read_b64_tr_b16 v[8:9], v10 offset:38912
	ds_read_b64_tr_b16 v[212:213], v10 offset:40960
	ds_read_b64_tr_b16 v[214:215], v10 offset:43008
	ds_read_b64_tr_b16 v[216:217], v10 offset:45056
	ds_read_b64_tr_b16 v[218:219], v10 offset:47104
	v_sub_f32_e32 v88, v93, v192
	v_exp_f32_e32 v88, v88
	v_add_f32_e32 v91, v85, v87
	v_cvt_pk_bf16_f32 v205, v81, v86
	v_cvt_pk_bf16_f32 v206, v85, v90
	v_add_f32_e32 v92, v90, v88
	v_add_f32_e32 v93, v91, v89
	v_sub_f32_e32 v89, v110, v192
	v_add_f32_e32 v93, v92, v93
	v_sub_f32_e32 v91, v94, v192
	v_sub_f32_e32 v92, v111, v192
	v_exp_f32_e32 v89, v89
	v_exp_f32_e32 v91, v91
	v_exp_f32_e32 v94, v92
	v_sub_f32_e32 v92, v95, v192
	v_exp_f32_e32 v92, v92
	v_add_f32_e32 v95, v89, v91
	v_cvt_pk_bf16_f32 v207, v89, v94
	v_cvt_pk_bf16_f32 v208, v15, v80
	v_add_f32_e32 v96, v94, v92
	v_add_f32_e32 v97, v95, v93
	v_cvt_pk_bf16_f32 v209, v83, v84
	v_add_f32_e32 v93, v96, v97
	v_add_f32_e32 v162, v162, v93
	v_cvt_pk_bf16_f32 v210, v87, v88
	v_cvt_pk_bf16_f32 v211, v91, v92
	s_waitcnt vmcnt(4)
	s_cmp_lg_u32 s41, 0
	s_barrier
	s_cbranch_scc1 .Lfx_fast
	s_mov_b64 s[80:81], -1
.Lfx_exit_adv:
	s_add_i32 s41, s41, -1
	s_xor_b32 s76, s76, 0x10200
	s_xor_b32 s77, s77, 0x10200
	s_andn2_b64 vcc, exec, s[80:81]
	s_cbranch_vccnz .Lfx_tail_skip
	s_add_i32 s64, s77, s51
	v_add_u32_e32 v10, s64, v183
	v_add_u32_e32 v11, s64, v184
	v_add_u32_e32 v12, s64, v185
	v_add_u32_e32 v13, s64, v186
	s_waitcnt lgkmcnt(6)
	v_mfma_f32_32x32x16_bf16 v[64:79], v[2:5], v[196:199], v[64:79]
	ds_read_b64_tr_b16 v[220:221], v11 offset:32768
	ds_read_b64_tr_b16 v[222:223], v11 offset:34816
	s_waitcnt lgkmcnt(6)
	v_mfma_f32_32x32x16_bf16 v[64:79], v[6:9], v[204:207], v[64:79]
	ds_read_b64_tr_b16 v[224:225], v11 offset:36864
	ds_read_b64_tr_b16 v[226:227], v11 offset:38912
	s_waitcnt lgkmcnt(6)
	v_mfma_f32_32x32x16_bf16 v[64:79], v[212:215], v[200:203], v[64:79]
	ds_read_b64_tr_b16 v[228:229], v11 offset:40960
	ds_read_b64_tr_b16 v[230:231], v11 offset:43008
	s_waitcnt lgkmcnt(6)
	v_mfma_f32_32x32x16_bf16 v[64:79], v[216:219], v[208:211], v[64:79]
	ds_read_b64_tr_b16 v[232:233], v11 offset:45056
	ds_read_b64_tr_b16 v[234:235], v11 offset:47104
	s_waitcnt lgkmcnt(6)
	v_mfma_f32_32x32x16_bf16 v[48:63], v[220:223], v[196:199], v[48:63]
	ds_read_b64_tr_b16 v[2:3], v12 offset:32768
	ds_read_b64_tr_b16 v[4:5], v12 offset:34816
	s_waitcnt lgkmcnt(6)
	v_mfma_f32_32x32x16_bf16 v[48:63], v[224:227], v[204:207], v[48:63]
	ds_read_b64_tr_b16 v[6:7], v12 offset:36864
	ds_read_b64_tr_b16 v[8:9], v12 offset:38912
	s_waitcnt lgkmcnt(6)
	v_mfma_f32_32x32x16_bf16 v[48:63], v[228:231], v[200:203], v[48:63]
	ds_read_b64_tr_b16 v[212:213], v12 offset:40960
	ds_read_b64_tr_b16 v[214:215], v12 offset:43008
	s_waitcnt lgkmcnt(6)
	v_mfma_f32_32x32x16_bf16 v[48:63], v[232:235], v[208:211], v[48:63]
	ds_read_b64_tr_b16 v[216:217], v12 offset:45056
	ds_read_b64_tr_b16 v[218:219], v12 offset:47104
	s_waitcnt lgkmcnt(6)
	v_mfma_f32_32x32x16_bf16 v[32:47], v[2:5], v[196:199], v[32:47]
	ds_read_b64_tr_b16 v[220:221], v13 offset:32768
	ds_read_b64_tr_b16 v[222:223], v13 offset:34816
	s_waitcnt lgkmcnt(6)
	v_mfma_f32_32x32x16_bf16 v[32:47], v[6:9], v[204:207], v[32:47]
	ds_read_b64_tr_b16 v[224:225], v13 offset:36864
	ds_read_b64_tr_b16 v[226:227], v13 offset:38912
	s_waitcnt lgkmcnt(6)
	v_mfma_f32_32x32x16_bf16 v[32:47], v[212:215], v[200:203], v[32:47]
	ds_read_b64_tr_b16 v[228:229], v13 offset:40960
	ds_read_b64_tr_b16 v[230:231], v13 offset:43008
	s_waitcnt lgkmcnt(6)
	v_mfma_f32_32x32x16_bf16 v[32:47], v[216:219], v[208:211], v[32:47]
	ds_read_b64_tr_b16 v[232:233], v13 offset:45056
	ds_read_b64_tr_b16 v[234:235], v13 offset:47104
	s_waitcnt lgkmcnt(6)
	v_mfma_f32_32x32x16_bf16 v[16:31], v[220:223], v[196:199], v[16:31]
	s_waitcnt lgkmcnt(4)
	v_mfma_f32_32x32x16_bf16 v[16:31], v[224:227], v[204:207], v[16:31]
	s_waitcnt lgkmcnt(2)
	v_mfma_f32_32x32x16_bf16 v[16:31], v[228:231], v[200:203], v[16:31]
	s_waitcnt lgkmcnt(0)
	v_mfma_f32_32x32x16_bf16 v[16:31], v[232:235], v[208:211], v[16:31]
	s_waitcnt vmcnt(0)

.Lfx_resc_fv:
	v_max_f32_e32 v0, v0, v0
	v_max_f32_e32 v2, v192, v192
	v_max_f32_e32 v2, v2, v0
	v_sub_f32_e32 v0, v192, v2
	v_exp_f32_e32 v0, v0
	v_mov_b32_e32 v192, v2
	v_mul_f32_e32 v162, v162, v0
	v_pk_mul_f32 v[78:79], v[78:79], v[0:1] op_sel_hi:[1,0]
	v_pk_mul_f32 v[76:77], v[76:77], v[0:1] op_sel_hi:[1,0]
	v_pk_mul_f32 v[74:75], v[74:75], v[0:1] op_sel_hi:[1,0]
	v_pk_mul_f32 v[72:73], v[72:73], v[0:1] op_sel_hi:[1,0]
	v_pk_mul_f32 v[70:71], v[70:71], v[0:1] op_sel_hi:[1,0]
	v_pk_mul_f32 v[68:69], v[68:69], v[0:1] op_sel_hi:[1,0]
	v_pk_mul_f32 v[66:67], v[66:67], v[0:1] op_sel_hi:[1,0]
	v_pk_mul_f32 v[64:65], v[64:65], v[0:1] op_sel_hi:[1,0]
	v_pk_mul_f32 v[62:63], v[62:63], v[0:1] op_sel_hi:[1,0]
	v_pk_mul_f32 v[60:61], v[60:61], v[0:1] op_sel_hi:[1,0]
	v_pk_mul_f32 v[58:59], v[58:59], v[0:1] op_sel_hi:[1,0]
	v_pk_mul_f32 v[56:57], v[56:57], v[0:1] op_sel_hi:[1,0]
	v_pk_mul_f32 v[54:55], v[54:55], v[0:1] op_sel_hi:[1,0]
	v_pk_mul_f32 v[52:53], v[52:53], v[0:1] op_sel_hi:[1,0]
	v_pk_mul_f32 v[50:51], v[50:51], v[0:1] op_sel_hi:[1,0]
	v_pk_mul_f32 v[48:49], v[48:49], v[0:1] op_sel_hi:[1,0]
	v_pk_mul_f32 v[46:47], v[46:47], v[0:1] op_sel_hi:[1,0]
	v_pk_mul_f32 v[44:45], v[44:45], v[0:1] op_sel_hi:[1,0]
	v_pk_mul_f32 v[42:43], v[42:43], v[0:1] op_sel_hi:[1,0]
	v_pk_mul_f32 v[40:41], v[40:41], v[0:1] op_sel_hi:[1,0]
	v_pk_mul_f32 v[38:39], v[38:39], v[0:1] op_sel_hi:[1,0]
	v_pk_mul_f32 v[36:37], v[36:37], v[0:1] op_sel_hi:[1,0]
	v_pk_mul_f32 v[34:35], v[34:35], v[0:1] op_sel_hi:[1,0]
	v_pk_mul_f32 v[32:33], v[32:33], v[0:1] op_sel_hi:[1,0]
	v_pk_mul_f32 v[30:31], v[30:31], v[0:1] op_sel_hi:[1,0]
	v_pk_mul_f32 v[28:29], v[28:29], v[0:1] op_sel_hi:[1,0]
	v_pk_mul_f32 v[26:27], v[26:27], v[0:1] op_sel_hi:[1,0]
	v_pk_mul_f32 v[24:25], v[24:25], v[0:1] op_sel_hi:[1,0]
	v_pk_mul_f32 v[22:23], v[22:23], v[0:1] op_sel_hi:[1,0]
	v_pk_mul_f32 v[20:21], v[20:21], v[0:1] op_sel_hi:[1,0]
	v_pk_mul_f32 v[18:19], v[18:19], v[0:1] op_sel_hi:[1,0]
	v_pk_mul_f32 v[16:17], v[16:17], v[0:1] op_sel_hi:[1,0]
	s_branch .Lfx_sm_exp_fv
